# P5 row loop: three items per trip with all their loads in flight
# baseline (speedup 1.0000x reference)
.LBB0_1613:
	v_readfirstlane_b32 s84, v3
	s_nop 0
	s_add_i32 s84, s84, s12
	s_cmp_gt_i32 s84, s14
	s_cbranch_scc1 .Lp5_single
	s_add_i32 s84, s84, s12
	s_cmp_gt_i32 s84, s14
	s_cbranch_scc1 .Lp5_pair
	s_waitcnt vmcnt(6)
	v_ashrrev_i32_e32 v26, 1, v3
	v_ashrrev_i32_e32 v27, 31, v26
	v_lshlrev_b64 v[28:29], 11, v[26:27]
	v_lshlrev_b64 v[26:27], 6, v[26:27]
	v_lshl_or_b32 v28, v2, 1, v28
	s_waitcnt vmcnt(4)
	v_lshl_add_u64 v[38:39], v[4:5], 0, v[26:27]
	v_lshl_add_u64 v[40:41], s[4:5], 0, v[28:29]
	v_lshl_add_u64 v[30:31], s[6:7], 0, v[28:29]
	v_lshl_add_u64 v[34:35], s[8:9], 0, v[28:29]
	global_load_dwordx4 v[10:13], v[6:7], off offset:16
	global_load_dwordx4 v[14:17], v[6:7], off
	global_load_dwordx4 v[18:21], v[8:9], off offset:16
	global_load_dwordx4 v[22:25], v[8:9], off
	global_load_dwordx4 v[26:29], v[40:41], off
	s_nop 0
	global_load_dwordx4 v[30:33], v[30:31], off
	s_nop 0
	global_load_dwordx4 v[34:37], v[34:35], off
	s_nop 0
	global_load_dword v38, v[38:39], off
	v_add_u32_e32 v126, s12, v3
	v_ashrrev_i32_e32 v90, 1, v126
	v_ashrrev_i32_e32 v91, 31, v90
	v_lshlrev_b64 v[92:93], 11, v[90:91]
	v_lshlrev_b64 v[90:91], 6, v[90:91]
	v_lshl_or_b32 v92, v2, 1, v92
	v_lshl_add_u64 v[102:103], v[4:5], 0, v[90:91]
	v_lshl_add_u64 v[104:105], s[4:5], 0, v[92:93]
	v_lshl_add_u64 v[94:95], s[6:7], 0, v[92:93]
	v_lshl_add_u64 v[98:99], s[8:9], 0, v[92:93]
	global_load_dwordx4 v[74:77], v[6:7], off offset:16
	global_load_dwordx4 v[78:81], v[6:7], off
	global_load_dwordx4 v[82:85], v[8:9], off offset:16
	global_load_dwordx4 v[86:89], v[8:9], off
	global_load_dwordx4 v[90:93], v[104:105], off
	s_nop 0
	global_load_dwordx4 v[94:97], v[94:95], off
	s_nop 0
	global_load_dwordx4 v[98:101], v[98:99], off
	s_nop 0
	global_load_dword v102, v[102:103], off
	v_add_u32_e32 v127, s12, v126
	v_ashrrev_i32_e32 v196, 1, v127
	v_ashrrev_i32_e32 v197, 31, v196
	v_lshlrev_b64 v[198:199], 11, v[196:197]
	v_lshlrev_b64 v[196:197], 6, v[196:197]
	v_lshl_or_b32 v198, v2, 1, v198
	v_lshl_add_u64 v[208:209], v[4:5], 0, v[196:197]
	v_lshl_add_u64 v[210:211], s[4:5], 0, v[198:199]
	v_lshl_add_u64 v[200:201], s[6:7], 0, v[198:199]
	v_lshl_add_u64 v[204:205], s[8:9], 0, v[198:199]
	global_load_dwordx4 v[180:183], v[6:7], off offset:16
	global_load_dwordx4 v[184:187], v[6:7], off
	global_load_dwordx4 v[188:191], v[8:9], off offset:16
	global_load_dwordx4 v[192:195], v[8:9], off
	global_load_dwordx4 v[196:199], v[210:211], off
	s_nop 0
	global_load_dwordx4 v[200:203], v[200:201], off
	s_nop 0
	global_load_dwordx4 v[204:207], v[204:205], off
	s_nop 0
	global_load_dword v208, v[208:209], off
	v_add_u32_e32 v3, s12, v127
	v_cmp_lt_i32_e32 vcc, s14, v3
	s_or_b64 s[10:11], vcc, s[10:11]
	s_waitcnt vmcnt(19)
	v_lshlrev_b32_e32 v42, 16, v26
	v_and_b32_e32 v43, 0xffff0000, v26
	v_add_f32_e32 v39, 0, v42
	v_lshlrev_b32_e32 v26, 16, v27
	v_add_f32_e32 v39, v39, v43
	v_and_b32_e32 v27, 0xffff0000, v27
	v_add_f32_e32 v39, v39, v26
	v_lshlrev_b32_e32 v44, 16, v28
	v_add_f32_e32 v39, v39, v27
	v_and_b32_e32 v45, 0xffff0000, v28
	v_add_f32_e32 v39, v39, v44
	v_lshlrev_b32_e32 v28, 16, v29
	v_add_f32_e32 v39, v39, v45
	v_and_b32_e32 v29, 0xffff0000, v29
	v_add_f32_e32 v39, v39, v28
	v_add_f32_e32 v39, v39, v29
	s_waitcnt vmcnt(18)
	v_lshlrev_b32_e32 v46, 16, v30
	v_and_b32_e32 v47, 0xffff0000, v30
	v_add_f32_dpp v39, v39, v39 quad_perm:[1,0,3,2] row_mask:0xf bank_mask:0xf bound_ctrl:1
	v_lshlrev_b32_e32 v30, 16, v31
	v_and_b32_e32 v31, 0xffff0000, v31
	v_add_f32_dpp v39, v39, v39 quad_perm:[2,3,0,1] row_mask:0xf bank_mask:0xf bound_ctrl:1
	v_lshlrev_b32_e32 v48, 16, v32
	v_and_b32_e32 v49, 0xffff0000, v32
	v_add_f32_dpp v39, v39, v39 row_half_mirror row_mask:0xf bank_mask:0xf bound_ctrl:1
	v_mul_f32_e32 v54, 0x3c800000, v39
	v_pk_add_f32 v[42:43], v[42:43], v[54:55] op_sel_hi:[1,0] neg_lo:[0,1] neg_hi:[0,1]
	v_pk_add_f32 v[26:27], v[26:27], v[54:55] op_sel_hi:[1,0] neg_lo:[0,1] neg_hi:[0,1]
	v_pk_add_f32 v[44:45], v[44:45], v[54:55] op_sel_hi:[1,0] neg_lo:[0,1] neg_hi:[0,1]
	v_pk_add_f32 v[28:29], v[28:29], v[54:55] op_sel_hi:[1,0] neg_lo:[0,1] neg_hi:[0,1]
	v_pk_mul_f32 v[54:55], v[42:43], v[42:43]
	v_pk_mul_f32 v[56:57], v[26:27], v[26:27]
	v_add_f32_e32 v39, v54, v55
	v_add_f32_e32 v39, v56, v39
	v_pk_mul_f32 v[58:59], v[44:45], v[44:45]
	v_add_f32_e32 v39, v57, v39
	v_add_f32_e32 v39, v58, v39
	v_pk_mul_f32 v[60:61], v[28:29], v[28:29]
	v_add_f32_e32 v39, v59, v39
	v_add_f32_e32 v39, v60, v39
	v_add_f32_e32 v39, v61, v39
	v_lshlrev_b32_e32 v32, 16, v33
	v_and_b32_e32 v33, 0xffff0000, v33
	v_add_f32_dpp v39, v39, v39 quad_perm:[1,0,3,2] row_mask:0xf bank_mask:0xf bound_ctrl:1
	s_waitcnt vmcnt(17)
	v_lshlrev_b32_e32 v50, 16, v34
	v_and_b32_e32 v51, 0xffff0000, v34
	v_add_f32_dpp v39, v39, v39 quad_perm:[2,3,0,1] row_mask:0xf bank_mask:0xf bound_ctrl:1
	v_lshlrev_b32_e32 v34, 16, v35
	v_and_b32_e32 v35, 0xffff0000, v35
	v_add_f32_dpp v39, v39, v39 row_half_mirror row_mask:0xf bank_mask:0xf bound_ctrl:1
	v_fmamk_f32 v39, v39, 0x3c800000, v1
	v_mul_f32_e32 v54, 0x4b800000, v39
	v_cmp_gt_f32_e32 vcc, s13, v39
	v_lshlrev_b32_e32 v52, 16, v36
	v_and_b32_e32 v53, 0xffff0000, v36
	v_cndmask_b32_e32 v39, v39, v54, vcc
	v_rsq_f32_e32 v39, v39
	v_lshlrev_b32_e32 v36, 16, v37
	v_and_b32_e32 v37, 0xffff0000, v37
	v_mul_f32_e32 v54, 0x45800000, v39
	v_cndmask_b32_e32 v54, v39, v54, vcc
	v_pk_mul_f32 v[42:43], v[42:43], v[54:55] op_sel_hi:[1,0]
	v_pk_mul_f32 v[26:27], v[26:27], v[54:55] op_sel_hi:[1,0]
	v_pk_mul_f32 v[44:45], v[44:45], v[54:55] op_sel_hi:[1,0]
	v_pk_mul_f32 v[28:29], v[28:29], v[54:55] op_sel_hi:[1,0]
	v_pk_fma_f32 v[14:15], v[14:15], v[42:43], v[22:23]
	v_pk_fma_f32 v[16:17], v[16:17], v[26:27], v[24:25]
	v_pk_fma_f32 v[10:11], v[10:11], v[44:45], v[18:19]
	v_pk_fma_f32 v[12:13], v[12:13], v[28:29], v[20:21]
	s_waitcnt vmcnt(16)
	v_pk_fma_f32 v[14:15], v[38:39], v[46:47], v[14:15] op_sel_hi:[0,1,1]
	v_pk_fma_f32 v[16:17], v[38:39], v[30:31], v[16:17] op_sel_hi:[0,1,1]
	v_pk_fma_f32 v[10:11], v[38:39], v[48:49], v[10:11] op_sel_hi:[0,1,1]
	v_pk_fma_f32 v[12:13], v[38:39], v[32:33], v[12:13] op_sel_hi:[0,1,1]
	v_pk_mul_f32 v[14:15], v[14:15], v[50:51]
	v_pk_mul_f32 v[16:17], v[16:17], v[34:35]
	v_pk_mul_f32 v[18:19], v[10:11], v[52:53]
	v_pk_mul_f32 v[20:21], v[12:13], v[36:37]
	v_cvt_pk_bf16_f32 v10, v14, v15
	v_cvt_pk_bf16_f32 v11, v16, v17
	v_cvt_pk_bf16_f32 v12, v18, v19
	v_cvt_pk_bf16_f32 v13, v20, v21
	global_store_dwordx4 v[40:41], v[10:13], off
	s_waitcnt vmcnt(12)
	v_lshlrev_b32_e32 v106, 16, v90
	v_and_b32_e32 v107, 0xffff0000, v90
	v_add_f32_e32 v103, 0, v106
	v_lshlrev_b32_e32 v90, 16, v91
	v_add_f32_e32 v103, v103, v107
	v_and_b32_e32 v91, 0xffff0000, v91
	v_add_f32_e32 v103, v103, v90
	v_lshlrev_b32_e32 v108, 16, v92
	v_add_f32_e32 v103, v103, v91
	v_and_b32_e32 v109, 0xffff0000, v92
	v_add_f32_e32 v103, v103, v108
	v_lshlrev_b32_e32 v92, 16, v93
	v_add_f32_e32 v103, v103, v109
	v_and_b32_e32 v93, 0xffff0000, v93
	v_add_f32_e32 v103, v103, v92
	v_add_f32_e32 v103, v103, v93
	s_waitcnt vmcnt(11)
	v_lshlrev_b32_e32 v110, 16, v94
	v_and_b32_e32 v111, 0xffff0000, v94
	v_add_f32_dpp v103, v103, v103 quad_perm:[1,0,3,2] row_mask:0xf bank_mask:0xf bound_ctrl:1
	v_lshlrev_b32_e32 v94, 16, v95
	v_and_b32_e32 v95, 0xffff0000, v95
	v_add_f32_dpp v103, v103, v103 quad_perm:[2,3,0,1] row_mask:0xf bank_mask:0xf bound_ctrl:1
	v_lshlrev_b32_e32 v112, 16, v96
	v_and_b32_e32 v113, 0xffff0000, v96
	v_add_f32_dpp v103, v103, v103 row_half_mirror row_mask:0xf bank_mask:0xf bound_ctrl:1
	v_mul_f32_e32 v118, 0x3c800000, v103
	v_pk_add_f32 v[106:107], v[106:107], v[118:119] op_sel_hi:[1,0] neg_lo:[0,1] neg_hi:[0,1]
	v_pk_add_f32 v[90:91], v[90:91], v[118:119] op_sel_hi:[1,0] neg_lo:[0,1] neg_hi:[0,1]
	v_pk_add_f32 v[108:109], v[108:109], v[118:119] op_sel_hi:[1,0] neg_lo:[0,1] neg_hi:[0,1]
	v_pk_add_f32 v[92:93], v[92:93], v[118:119] op_sel_hi:[1,0] neg_lo:[0,1] neg_hi:[0,1]
	v_pk_mul_f32 v[118:119], v[106:107], v[106:107]
	v_pk_mul_f32 v[120:121], v[90:91], v[90:91]
	v_add_f32_e32 v103, v118, v119
	v_add_f32_e32 v103, v120, v103
	v_pk_mul_f32 v[122:123], v[108:109], v[108:109]
	v_add_f32_e32 v103, v121, v103
	v_add_f32_e32 v103, v122, v103
	v_pk_mul_f32 v[124:125], v[92:93], v[92:93]
	v_add_f32_e32 v103, v123, v103
	v_add_f32_e32 v103, v124, v103
	v_add_f32_e32 v103, v125, v103
	v_lshlrev_b32_e32 v96, 16, v97
	v_and_b32_e32 v97, 0xffff0000, v97
	v_add_f32_dpp v103, v103, v103 quad_perm:[1,0,3,2] row_mask:0xf bank_mask:0xf bound_ctrl:1
	s_waitcnt vmcnt(10)
	v_lshlrev_b32_e32 v114, 16, v98
	v_and_b32_e32 v115, 0xffff0000, v98
	v_add_f32_dpp v103, v103, v103 quad_perm:[2,3,0,1] row_mask:0xf bank_mask:0xf bound_ctrl:1
	v_lshlrev_b32_e32 v98, 16, v99
	v_and_b32_e32 v99, 0xffff0000, v99
	v_add_f32_dpp v103, v103, v103 row_half_mirror row_mask:0xf bank_mask:0xf bound_ctrl:1
	v_fmamk_f32 v103, v103, 0x3c800000, v1
	v_mul_f32_e32 v118, 0x4b800000, v103
	v_cmp_gt_f32_e32 vcc, s13, v103
	v_lshlrev_b32_e32 v116, 16, v100
	v_and_b32_e32 v117, 0xffff0000, v100
	v_cndmask_b32_e32 v103, v103, v118, vcc
	v_rsq_f32_e32 v103, v103
	v_lshlrev_b32_e32 v100, 16, v101
	v_and_b32_e32 v101, 0xffff0000, v101
	v_mul_f32_e32 v118, 0x45800000, v103
	v_cndmask_b32_e32 v118, v103, v118, vcc
	v_pk_mul_f32 v[106:107], v[106:107], v[118:119] op_sel_hi:[1,0]
	v_pk_mul_f32 v[90:91], v[90:91], v[118:119] op_sel_hi:[1,0]
	v_pk_mul_f32 v[108:109], v[108:109], v[118:119] op_sel_hi:[1,0]
	v_pk_mul_f32 v[92:93], v[92:93], v[118:119] op_sel_hi:[1,0]
	v_pk_fma_f32 v[78:79], v[78:79], v[106:107], v[86:87]
	v_pk_fma_f32 v[80:81], v[80:81], v[90:91], v[88:89]
	v_pk_fma_f32 v[74:75], v[74:75], v[108:109], v[82:83]
	v_pk_fma_f32 v[76:77], v[76:77], v[92:93], v[84:85]
	s_waitcnt vmcnt(9)
	v_pk_fma_f32 v[78:79], v[102:103], v[110:111], v[78:79] op_sel_hi:[0,1,1]
	v_pk_fma_f32 v[80:81], v[102:103], v[94:95], v[80:81] op_sel_hi:[0,1,1]
	v_pk_fma_f32 v[74:75], v[102:103], v[112:113], v[74:75] op_sel_hi:[0,1,1]
	v_pk_fma_f32 v[76:77], v[102:103], v[96:97], v[76:77] op_sel_hi:[0,1,1]
	v_pk_mul_f32 v[78:79], v[78:79], v[114:115]
	v_pk_mul_f32 v[80:81], v[80:81], v[98:99]
	v_pk_mul_f32 v[82:83], v[74:75], v[116:117]
	v_pk_mul_f32 v[84:85], v[76:77], v[100:101]
	v_cvt_pk_bf16_f32 v74, v78, v79
	v_cvt_pk_bf16_f32 v75, v80, v81
	v_cvt_pk_bf16_f32 v76, v82, v83
	v_cvt_pk_bf16_f32 v77, v84, v85
	global_store_dwordx4 v[104:105], v[74:77], off
	s_waitcnt vmcnt(5)
	v_lshlrev_b32_e32 v212, 16, v196
	v_and_b32_e32 v213, 0xffff0000, v196
	v_add_f32_e32 v209, 0, v212
	v_lshlrev_b32_e32 v196, 16, v197
	v_add_f32_e32 v209, v209, v213
	v_and_b32_e32 v197, 0xffff0000, v197
	v_add_f32_e32 v209, v209, v196
	v_lshlrev_b32_e32 v214, 16, v198
	v_add_f32_e32 v209, v209, v197
	v_and_b32_e32 v215, 0xffff0000, v198
	v_add_f32_e32 v209, v209, v214
	v_lshlrev_b32_e32 v198, 16, v199
	v_add_f32_e32 v209, v209, v215
	v_and_b32_e32 v199, 0xffff0000, v199
	v_add_f32_e32 v209, v209, v198
	v_add_f32_e32 v209, v209, v199
	s_waitcnt vmcnt(4)
	v_lshlrev_b32_e32 v216, 16, v200
	v_and_b32_e32 v217, 0xffff0000, v200
	v_add_f32_dpp v209, v209, v209 quad_perm:[1,0,3,2] row_mask:0xf bank_mask:0xf bound_ctrl:1
	v_lshlrev_b32_e32 v200, 16, v201
	v_and_b32_e32 v201, 0xffff0000, v201
	v_add_f32_dpp v209, v209, v209 quad_perm:[2,3,0,1] row_mask:0xf bank_mask:0xf bound_ctrl:1
	v_lshlrev_b32_e32 v218, 16, v202
	v_and_b32_e32 v219, 0xffff0000, v202
	v_add_f32_dpp v209, v209, v209 row_half_mirror row_mask:0xf bank_mask:0xf bound_ctrl:1
	v_mul_f32_e32 v224, 0x3c800000, v209
	v_pk_add_f32 v[212:213], v[212:213], v[224:225] op_sel_hi:[1,0] neg_lo:[0,1] neg_hi:[0,1]
	v_pk_add_f32 v[196:197], v[196:197], v[224:225] op_sel_hi:[1,0] neg_lo:[0,1] neg_hi:[0,1]
	v_pk_add_f32 v[214:215], v[214:215], v[224:225] op_sel_hi:[1,0] neg_lo:[0,1] neg_hi:[0,1]
	v_pk_add_f32 v[198:199], v[198:199], v[224:225] op_sel_hi:[1,0] neg_lo:[0,1] neg_hi:[0,1]
	v_pk_mul_f32 v[224:225], v[212:213], v[212:213]
	v_pk_mul_f32 v[226:227], v[196:197], v[196:197]
	v_add_f32_e32 v209, v224, v225
	v_add_f32_e32 v209, v226, v209
	v_pk_mul_f32 v[228:229], v[214:215], v[214:215]
	v_add_f32_e32 v209, v227, v209
	v_add_f32_e32 v209, v228, v209
	v_pk_mul_f32 v[230:231], v[198:199], v[198:199]
	v_add_f32_e32 v209, v229, v209
	v_add_f32_e32 v209, v230, v209
	v_add_f32_e32 v209, v231, v209
	v_lshlrev_b32_e32 v202, 16, v203
	v_and_b32_e32 v203, 0xffff0000, v203
	v_add_f32_dpp v209, v209, v209 quad_perm:[1,0,3,2] row_mask:0xf bank_mask:0xf bound_ctrl:1
	s_waitcnt vmcnt(3)
	v_lshlrev_b32_e32 v220, 16, v204
	v_and_b32_e32 v221, 0xffff0000, v204
	v_add_f32_dpp v209, v209, v209 quad_perm:[2,3,0,1] row_mask:0xf bank_mask:0xf bound_ctrl:1
	v_lshlrev_b32_e32 v204, 16, v205
	v_and_b32_e32 v205, 0xffff0000, v205
	v_add_f32_dpp v209, v209, v209 row_half_mirror row_mask:0xf bank_mask:0xf bound_ctrl:1
	v_fmamk_f32 v209, v209, 0x3c800000, v1
	v_mul_f32_e32 v224, 0x4b800000, v209
	v_cmp_gt_f32_e32 vcc, s13, v209
	v_lshlrev_b32_e32 v222, 16, v206
	v_and_b32_e32 v223, 0xffff0000, v206
	v_cndmask_b32_e32 v209, v209, v224, vcc
	v_rsq_f32_e32 v209, v209
	v_lshlrev_b32_e32 v206, 16, v207
	v_and_b32_e32 v207, 0xffff0000, v207
	v_mul_f32_e32 v224, 0x45800000, v209
	v_cndmask_b32_e32 v224, v209, v224, vcc
	v_pk_mul_f32 v[212:213], v[212:213], v[224:225] op_sel_hi:[1,0]
	v_pk_mul_f32 v[196:197], v[196:197], v[224:225] op_sel_hi:[1,0]
	v_pk_mul_f32 v[214:215], v[214:215], v[224:225] op_sel_hi:[1,0]
	v_pk_mul_f32 v[198:199], v[198:199], v[224:225] op_sel_hi:[1,0]
	v_pk_fma_f32 v[184:185], v[184:185], v[212:213], v[192:193]
	v_pk_fma_f32 v[186:187], v[186:187], v[196:197], v[194:195]
	v_pk_fma_f32 v[180:181], v[180:181], v[214:215], v[188:189]
	v_pk_fma_f32 v[182:183], v[182:183], v[198:199], v[190:191]
	s_waitcnt vmcnt(2)
	v_pk_fma_f32 v[184:185], v[208:209], v[216:217], v[184:185] op_sel_hi:[0,1,1]
	v_pk_fma_f32 v[186:187], v[208:209], v[200:201], v[186:187] op_sel_hi:[0,1,1]
	v_pk_fma_f32 v[180:181], v[208:209], v[218:219], v[180:181] op_sel_hi:[0,1,1]
	v_pk_fma_f32 v[182:183], v[208:209], v[202:203], v[182:183] op_sel_hi:[0,1,1]
	v_pk_mul_f32 v[184:185], v[184:185], v[220:221]
	v_pk_mul_f32 v[186:187], v[186:187], v[204:205]
	v_pk_mul_f32 v[188:189], v[180:181], v[222:223]
	v_pk_mul_f32 v[190:191], v[182:183], v[206:207]
	v_cvt_pk_bf16_f32 v180, v184, v185
	v_cvt_pk_bf16_f32 v181, v186, v187
	v_cvt_pk_bf16_f32 v182, v188, v189
	v_cvt_pk_bf16_f32 v183, v190, v191
	global_store_dwordx4 v[210:211], v[180:183], off
	s_andn2_b64 exec, exec, s[10:11]
	s_cbranch_execnz .LBB0_1613
	s_branch .LBB0_1614
.Lp5_pair:
	s_waitcnt vmcnt(6)
	v_ashrrev_i32_e32 v26, 1, v3
	v_ashrrev_i32_e32 v27, 31, v26
	v_lshlrev_b64 v[28:29], 11, v[26:27]
	v_lshlrev_b64 v[26:27], 6, v[26:27]
	v_lshl_or_b32 v28, v2, 1, v28
	s_waitcnt vmcnt(4)
	v_lshl_add_u64 v[38:39], v[4:5], 0, v[26:27]
	v_lshl_add_u64 v[40:41], s[4:5], 0, v[28:29]
	v_lshl_add_u64 v[30:31], s[6:7], 0, v[28:29]
	v_lshl_add_u64 v[34:35], s[8:9], 0, v[28:29]
	global_load_dwordx4 v[10:13], v[6:7], off offset:16
	global_load_dwordx4 v[14:17], v[6:7], off
	global_load_dwordx4 v[18:21], v[8:9], off offset:16
	global_load_dwordx4 v[22:25], v[8:9], off
	global_load_dwordx4 v[26:29], v[40:41], off
	s_nop 0
	global_load_dwordx4 v[30:33], v[30:31], off
	s_nop 0
	global_load_dwordx4 v[34:37], v[34:35], off
	s_nop 0
	global_load_dword v38, v[38:39], off
	v_add_u32_e32 v126, s12, v3
	v_ashrrev_i32_e32 v90, 1, v126
	v_ashrrev_i32_e32 v91, 31, v90
	v_lshlrev_b64 v[92:93], 11, v[90:91]
	v_lshlrev_b64 v[90:91], 6, v[90:91]
	v_lshl_or_b32 v92, v2, 1, v92
	v_lshl_add_u64 v[102:103], v[4:5], 0, v[90:91]
	v_lshl_add_u64 v[104:105], s[4:5], 0, v[92:93]
	v_lshl_add_u64 v[94:95], s[6:7], 0, v[92:93]
	v_lshl_add_u64 v[98:99], s[8:9], 0, v[92:93]
	global_load_dwordx4 v[74:77], v[6:7], off offset:16
	global_load_dwordx4 v[78:81], v[6:7], off
	global_load_dwordx4 v[82:85], v[8:9], off offset:16
	global_load_dwordx4 v[86:89], v[8:9], off
	global_load_dwordx4 v[90:93], v[104:105], off
	s_nop 0
	global_load_dwordx4 v[94:97], v[94:95], off
	s_nop 0
	global_load_dwordx4 v[98:101], v[98:99], off
	s_nop 0
	global_load_dword v102, v[102:103], off
	v_add_u32_e32 v3, s12, v126
	v_cmp_lt_i32_e32 vcc, s14, v3
	s_or_b64 s[10:11], vcc, s[10:11]
	s_waitcnt vmcnt(11)
	v_lshlrev_b32_e32 v42, 16, v26
	v_and_b32_e32 v43, 0xffff0000, v26
	v_add_f32_e32 v39, 0, v42
	v_lshlrev_b32_e32 v26, 16, v27
	v_add_f32_e32 v39, v39, v43
	v_and_b32_e32 v27, 0xffff0000, v27
	v_add_f32_e32 v39, v39, v26
	v_lshlrev_b32_e32 v44, 16, v28
	v_add_f32_e32 v39, v39, v27
	v_and_b32_e32 v45, 0xffff0000, v28
	v_add_f32_e32 v39, v39, v44
	v_lshlrev_b32_e32 v28, 16, v29
	v_add_f32_e32 v39, v39, v45
	v_and_b32_e32 v29, 0xffff0000, v29
	v_add_f32_e32 v39, v39, v28
	v_add_f32_e32 v39, v39, v29
	s_waitcnt vmcnt(10)
	v_lshlrev_b32_e32 v46, 16, v30
	v_and_b32_e32 v47, 0xffff0000, v30
	v_add_f32_dpp v39, v39, v39 quad_perm:[1,0,3,2] row_mask:0xf bank_mask:0xf bound_ctrl:1
	v_lshlrev_b32_e32 v30, 16, v31
	v_and_b32_e32 v31, 0xffff0000, v31
	v_add_f32_dpp v39, v39, v39 quad_perm:[2,3,0,1] row_mask:0xf bank_mask:0xf bound_ctrl:1
	v_lshlrev_b32_e32 v48, 16, v32
	v_and_b32_e32 v49, 0xffff0000, v32
	v_add_f32_dpp v39, v39, v39 row_half_mirror row_mask:0xf bank_mask:0xf bound_ctrl:1
	v_mul_f32_e32 v54, 0x3c800000, v39
	v_pk_add_f32 v[42:43], v[42:43], v[54:55] op_sel_hi:[1,0] neg_lo:[0,1] neg_hi:[0,1]
	v_pk_add_f32 v[26:27], v[26:27], v[54:55] op_sel_hi:[1,0] neg_lo:[0,1] neg_hi:[0,1]
	v_pk_add_f32 v[44:45], v[44:45], v[54:55] op_sel_hi:[1,0] neg_lo:[0,1] neg_hi:[0,1]
	v_pk_add_f32 v[28:29], v[28:29], v[54:55] op_sel_hi:[1,0] neg_lo:[0,1] neg_hi:[0,1]
	v_pk_mul_f32 v[54:55], v[42:43], v[42:43]
	v_pk_mul_f32 v[56:57], v[26:27], v[26:27]
	v_add_f32_e32 v39, v54, v55
	v_add_f32_e32 v39, v56, v39
	v_pk_mul_f32 v[58:59], v[44:45], v[44:45]
	v_add_f32_e32 v39, v57, v39
	v_add_f32_e32 v39, v58, v39
	v_pk_mul_f32 v[60:61], v[28:29], v[28:29]
	v_add_f32_e32 v39, v59, v39
	v_add_f32_e32 v39, v60, v39
	v_add_f32_e32 v39, v61, v39
	v_lshlrev_b32_e32 v32, 16, v33
	v_and_b32_e32 v33, 0xffff0000, v33
	v_add_f32_dpp v39, v39, v39 quad_perm:[1,0,3,2] row_mask:0xf bank_mask:0xf bound_ctrl:1
	s_waitcnt vmcnt(9)
	v_lshlrev_b32_e32 v50, 16, v34
	v_and_b32_e32 v51, 0xffff0000, v34
	v_add_f32_dpp v39, v39, v39 quad_perm:[2,3,0,1] row_mask:0xf bank_mask:0xf bound_ctrl:1
	v_lshlrev_b32_e32 v34, 16, v35
	v_and_b32_e32 v35, 0xffff0000, v35
	v_add_f32_dpp v39, v39, v39 row_half_mirror row_mask:0xf bank_mask:0xf bound_ctrl:1
	v_fmamk_f32 v39, v39, 0x3c800000, v1
	v_mul_f32_e32 v54, 0x4b800000, v39
	v_cmp_gt_f32_e32 vcc, s13, v39
	v_lshlrev_b32_e32 v52, 16, v36
	v_and_b32_e32 v53, 0xffff0000, v36
	v_cndmask_b32_e32 v39, v39, v54, vcc
	v_rsq_f32_e32 v39, v39
	v_lshlrev_b32_e32 v36, 16, v37
	v_and_b32_e32 v37, 0xffff0000, v37
	v_mul_f32_e32 v54, 0x45800000, v39
	v_cndmask_b32_e32 v54, v39, v54, vcc
	v_pk_mul_f32 v[42:43], v[42:43], v[54:55] op_sel_hi:[1,0]
	v_pk_mul_f32 v[26:27], v[26:27], v[54:55] op_sel_hi:[1,0]
	v_pk_mul_f32 v[44:45], v[44:45], v[54:55] op_sel_hi:[1,0]
	v_pk_mul_f32 v[28:29], v[28:29], v[54:55] op_sel_hi:[1,0]
	v_pk_fma_f32 v[14:15], v[14:15], v[42:43], v[22:23]
	v_pk_fma_f32 v[16:17], v[16:17], v[26:27], v[24:25]
	v_pk_fma_f32 v[10:11], v[10:11], v[44:45], v[18:19]
	v_pk_fma_f32 v[12:13], v[12:13], v[28:29], v[20:21]
	s_waitcnt vmcnt(8)
	v_pk_fma_f32 v[14:15], v[38:39], v[46:47], v[14:15] op_sel_hi:[0,1,1]
	v_pk_fma_f32 v[16:17], v[38:39], v[30:31], v[16:17] op_sel_hi:[0,1,1]
	v_pk_fma_f32 v[10:11], v[38:39], v[48:49], v[10:11] op_sel_hi:[0,1,1]
	v_pk_fma_f32 v[12:13], v[38:39], v[32:33], v[12:13] op_sel_hi:[0,1,1]
	v_pk_mul_f32 v[14:15], v[14:15], v[50:51]
	v_pk_mul_f32 v[16:17], v[16:17], v[34:35]
	v_pk_mul_f32 v[18:19], v[10:11], v[52:53]
	v_pk_mul_f32 v[20:21], v[12:13], v[36:37]
	v_cvt_pk_bf16_f32 v10, v14, v15
	v_cvt_pk_bf16_f32 v11, v16, v17
	v_cvt_pk_bf16_f32 v12, v18, v19
	v_cvt_pk_bf16_f32 v13, v20, v21
	global_store_dwordx4 v[40:41], v[10:13], off
	s_waitcnt vmcnt(4)
	v_lshlrev_b32_e32 v106, 16, v90
	v_and_b32_e32 v107, 0xffff0000, v90
	v_add_f32_e32 v103, 0, v106
	v_lshlrev_b32_e32 v90, 16, v91
	v_add_f32_e32 v103, v103, v107
	v_and_b32_e32 v91, 0xffff0000, v91
	v_add_f32_e32 v103, v103, v90
	v_lshlrev_b32_e32 v108, 16, v92
	v_add_f32_e32 v103, v103, v91
	v_and_b32_e32 v109, 0xffff0000, v92
	v_add_f32_e32 v103, v103, v108
	v_lshlrev_b32_e32 v92, 16, v93
	v_add_f32_e32 v103, v103, v109
	v_and_b32_e32 v93, 0xffff0000, v93
	v_add_f32_e32 v103, v103, v92
	v_add_f32_e32 v103, v103, v93
	s_waitcnt vmcnt(3)
	v_lshlrev_b32_e32 v110, 16, v94
	v_and_b32_e32 v111, 0xffff0000, v94
	v_add_f32_dpp v103, v103, v103 quad_perm:[1,0,3,2] row_mask:0xf bank_mask:0xf bound_ctrl:1
	v_lshlrev_b32_e32 v94, 16, v95
	v_and_b32_e32 v95, 0xffff0000, v95
	v_add_f32_dpp v103, v103, v103 quad_perm:[2,3,0,1] row_mask:0xf bank_mask:0xf bound_ctrl:1
	v_lshlrev_b32_e32 v112, 16, v96
	v_and_b32_e32 v113, 0xffff0000, v96
	v_add_f32_dpp v103, v103, v103 row_half_mirror row_mask:0xf bank_mask:0xf bound_ctrl:1
	v_mul_f32_e32 v118, 0x3c800000, v103
	v_pk_add_f32 v[106:107], v[106:107], v[118:119] op_sel_hi:[1,0] neg_lo:[0,1] neg_hi:[0,1]
	v_pk_add_f32 v[90:91], v[90:91], v[118:119] op_sel_hi:[1,0] neg_lo:[0,1] neg_hi:[0,1]
	v_pk_add_f32 v[108:109], v[108:109], v[118:119] op_sel_hi:[1,0] neg_lo:[0,1] neg_hi:[0,1]
	v_pk_add_f32 v[92:93], v[92:93], v[118:119] op_sel_hi:[1,0] neg_lo:[0,1] neg_hi:[0,1]
	v_pk_mul_f32 v[118:119], v[106:107], v[106:107]
	v_pk_mul_f32 v[120:121], v[90:91], v[90:91]
	v_add_f32_e32 v103, v118, v119
	v_add_f32_e32 v103, v120, v103
	v_pk_mul_f32 v[122:123], v[108:109], v[108:109]
	v_add_f32_e32 v103, v121, v103
	v_add_f32_e32 v103, v122, v103
	v_pk_mul_f32 v[124:125], v[92:93], v[92:93]
	v_add_f32_e32 v103, v123, v103
	v_add_f32_e32 v103, v124, v103
	v_add_f32_e32 v103, v125, v103
	v_lshlrev_b32_e32 v96, 16, v97
	v_and_b32_e32 v97, 0xffff0000, v97
	v_add_f32_dpp v103, v103, v103 quad_perm:[1,0,3,2] row_mask:0xf bank_mask:0xf bound_ctrl:1
	s_waitcnt vmcnt(2)
	v_lshlrev_b32_e32 v114, 16, v98
	v_and_b32_e32 v115, 0xffff0000, v98
	v_add_f32_dpp v103, v103, v103 quad_perm:[2,3,0,1] row_mask:0xf bank_mask:0xf bound_ctrl:1
	v_lshlrev_b32_e32 v98, 16, v99
	v_and_b32_e32 v99, 0xffff0000, v99
	v_add_f32_dpp v103, v103, v103 row_half_mirror row_mask:0xf bank_mask:0xf bound_ctrl:1
	v_fmamk_f32 v103, v103, 0x3c800000, v1
	v_mul_f32_e32 v118, 0x4b800000, v103
	v_cmp_gt_f32_e32 vcc, s13, v103
	v_lshlrev_b32_e32 v116, 16, v100
	v_and_b32_e32 v117, 0xffff0000, v100
	v_cndmask_b32_e32 v103, v103, v118, vcc
	v_rsq_f32_e32 v103, v103
	v_lshlrev_b32_e32 v100, 16, v101
	v_and_b32_e32 v101, 0xffff0000, v101
	v_mul_f32_e32 v118, 0x45800000, v103
	v_cndmask_b32_e32 v118, v103, v118, vcc
	v_pk_mul_f32 v[106:107], v[106:107], v[118:119] op_sel_hi:[1,0]
	v_pk_mul_f32 v[90:91], v[90:91], v[118:119] op_sel_hi:[1,0]
	v_pk_mul_f32 v[108:109], v[108:109], v[118:119] op_sel_hi:[1,0]
	v_pk_mul_f32 v[92:93], v[92:93], v[118:119] op_sel_hi:[1,0]
	v_pk_fma_f32 v[78:79], v[78:79], v[106:107], v[86:87]
	v_pk_fma_f32 v[80:81], v[80:81], v[90:91], v[88:89]
	v_pk_fma_f32 v[74:75], v[74:75], v[108:109], v[82:83]
	v_pk_fma_f32 v[76:77], v[76:77], v[92:93], v[84:85]
	s_waitcnt vmcnt(1)
	v_pk_fma_f32 v[78:79], v[102:103], v[110:111], v[78:79] op_sel_hi:[0,1,1]
	v_pk_fma_f32 v[80:81], v[102:103], v[94:95], v[80:81] op_sel_hi:[0,1,1]
	v_pk_fma_f32 v[74:75], v[102:103], v[112:113], v[74:75] op_sel_hi:[0,1,1]
	v_pk_fma_f32 v[76:77], v[102:103], v[96:97], v[76:77] op_sel_hi:[0,1,1]
	v_pk_mul_f32 v[78:79], v[78:79], v[114:115]
	v_pk_mul_f32 v[80:81], v[80:81], v[98:99]
	v_pk_mul_f32 v[82:83], v[74:75], v[116:117]
	v_pk_mul_f32 v[84:85], v[76:77], v[100:101]
	v_cvt_pk_bf16_f32 v74, v78, v79
	v_cvt_pk_bf16_f32 v75, v80, v81
	v_cvt_pk_bf16_f32 v76, v82, v83
	v_cvt_pk_bf16_f32 v77, v84, v85
	global_store_dwordx4 v[104:105], v[74:77], off
	s_andn2_b64 exec, exec, s[10:11]
	s_cbranch_execnz .LBB0_1613
	s_branch .LBB0_1614
